# baseline (speedup 1.0000x reference)
; template <int EPI, int AMAP, int KOFFMODE, int K>
; __device__ __forceinline__ void gemm_phase(unsigned char* smem, const bf16_t* A, int lda, const bf16_t* Bt, int NT, const EpiArgs& ea) {
;     ...
;         for (int kt = 0; kt < nk; ++kt) {
;             if (kt + 1 < nk) GEMM_DMA(m0, n0, kt + 1, cur ^ 1);
;             else if (have_next) GEMM_DMA(m0n, n0n, 0, cur ^ 1);
;             const unsigned char* Ac = smem + cur * STGB + (wm * 128 + l31) * 128;
;             const unsigned char* Bc = smem + cur * STGB + 32768 + (wn * 64 + l31) * 128;
;             bf16x8 fa[2][4], fb[2][2];
;             fb[0][0] = *(const bf16x8*)(Bc + (((0) ^ yz) & 7) * 16);
;             fb[0][1] = *(const bf16x8*)(Bc + 32 * 128 + (((0) ^ yz) & 7) * 16);
; #pragma unroll
;             for (int i = 0; i < 4; ++i) fa[0][i] = *(const bf16x8*)(Ac + i * 32 * 128 + (((0) ^ yz) & 7) * 16);
; #pragma unroll
;             for (int s = 0; s < 4; ++s) {
;                 if (s < 3) {
;                     const int o_ = (((2 * (s + 1)) ^ yz) & 7) * 16;
;                     fb[(s + 1) & 1][0] = *(const bf16x8*)(Bc + o_);
;                     fb[(s + 1) & 1][1] = *(const bf16x8*)(Bc + 32 * 128 + o_);
; #pragma unroll
;                     for (int i = 0; i < 4; ++i) fa[(s + 1) & 1][i] = *(const bf16x8*)(Ac + i * 32 * 128 + o_);
;                 }
; #pragma unroll
;                 for (int i = 0; i < 4; ++i) {
;                     acc[i][0] = __builtin_amdgcn_mfma_f32_32x32x16_bf16(fa[s & 1][i], fb[s & 1][0], acc[i][0], 0, 0, 0);
;                     acc[i][1] = __builtin_amdgcn_mfma_f32_32x32x16_bf16(fa[s & 1][i], fb[s & 1][1], acc[i][1], 0, 0, 0);
;                 }
;                 __builtin_amdgcn_sched_barrier(0);
;             }
;             if (kt + 1 < nk) asm volatile("s_waitcnt vmcnt(0)" ::: "memory");
;             __builtin_amdgcn_s_barrier();
.LBB0_461:
	s_mov_b32 s9, s13
	s_lshl_b32 s13, s9, 16
	s_xor_b32 s12, s13, 0x10000
	v_readfirstlane_b32 vcc_lo, v143
	s_nop 0
	s_add_u32 vcc_lo, vcc_lo, s12
	v_add3_u32 v155, s13, v150, v149
	v_add_u32_e32 v155, v155, v152
	v_add3_u32 v0, s13, v147, v149
	v_add_u32_e32 v0, v0, v152
	ds_read_b128 v[208:211], v155 offset:32768
	ds_read_b128 v[212:215], v155 offset:36864
	s_waitcnt lgkmcnt(5)
	v_mfma_f32_32x32x16_bf16 v[114:129], v[192:195], v[156:159], v[114:129]
	s_add_u32 s14, s4, 0xb240080
	s_addc_u32 s15, s5, 0
	s_mov_b32 m0, vcc_lo
	v_lshl_add_u64 v[164:165], v[136:137], 0, s[14:15]
	global_load_lds_dwordx4 v[164:165], off
	v_mfma_f32_32x32x16_bf16 v[98:113], v[192:195], v[160:163], v[98:113]
	s_add_u32 s14, s4, 0xb270080
	s_addc_u32 s15, s5, 0
	s_add_u32 m0, vcc_lo, 0x2000
	v_lshl_add_u64 v[164:165], v[136:137], 0, s[14:15]
	global_load_lds_dwordx4 v[164:165], off
	ds_read_b128 v[192:195], v0
	s_waitcnt lgkmcnt(5)
	v_mfma_f32_32x32x16_bf16 v[82:97], v[196:199], v[156:159], v[82:97]
	s_add_u32 s14, s4, 0xb2a0080
	s_addc_u32 s15, s5, 0
	s_add_u32 m0, vcc_lo, 0x4000
	v_lshl_add_u64 v[164:165], v[136:137], 0, s[14:15]
	global_load_lds_dwordx4 v[164:165], off
	v_mfma_f32_32x32x16_bf16 v[66:81], v[196:199], v[160:163], v[66:81]
	s_add_u32 s14, s4, 0xb2d0080
	s_addc_u32 s15, s5, 0
	s_add_u32 m0, vcc_lo, 0x6000
	v_lshl_add_u64 v[164:165], v[136:137], 0, s[14:15]
	global_load_lds_dwordx4 v[164:165], off
	ds_read_b128 v[196:199], v0 offset:4096
	s_waitcnt lgkmcnt(5)
	v_mfma_f32_32x32x16_bf16 v[50:65], v[200:203], v[156:159], v[50:65]
	v_mfma_f32_32x32x16_bf16 v[34:49], v[200:203], v[160:163], v[34:49]
	ds_read_b128 v[200:203], v0 offset:8192
	s_waitcnt lgkmcnt(5)
	v_mfma_f32_32x32x16_bf16 v[18:33], v[204:207], v[156:159], v[18:33]
	v_mfma_f32_32x32x16_bf16 v[2:17], v[204:207], v[160:163], v[2:17]
	ds_read_b128 v[204:207], v0 offset:12288
	v_add3_u32 v155, s13, v150, v149
	v_add_u32_e32 v155, v155, v153
	v_add3_u32 v0, s13, v147, v149
	v_add_u32_e32 v0, v0, v153
	ds_read_b128 v[156:159], v155 offset:32768
	ds_read_b128 v[160:163], v155 offset:36864
	s_waitcnt lgkmcnt(5)
	v_mfma_f32_32x32x16_bf16 v[114:129], v[192:195], v[208:211], v[114:129]
	v_mfma_f32_32x32x16_bf16 v[98:113], v[192:195], v[212:215], v[98:113]
	s_add_u32 s14, s4, 0xb00080
	s_addc_u32 s15, s5, 0
	s_add_u32 m0, vcc_lo, 0x8000
	v_lshl_add_u64 v[164:165], v[138:139], 0, s[14:15]
	global_load_lds_dwordx4 v[164:165], off
	ds_read_b128 v[192:195], v0
	s_waitcnt lgkmcnt(5)
	v_mfma_f32_32x32x16_bf16 v[82:97], v[196:199], v[208:211], v[82:97]
	v_mfma_f32_32x32x16_bf16 v[66:81], v[196:199], v[212:215], v[66:81]
	s_add_u32 s14, s4, 0xb30080
	s_addc_u32 s15, s5, 0
	s_add_u32 m0, vcc_lo, 0xa000
	v_lshl_add_u64 v[164:165], v[138:139], 0, s[14:15]
	global_load_lds_dwordx4 v[164:165], off
	ds_read_b128 v[196:199], v0 offset:4096
	s_waitcnt lgkmcnt(5)
	v_mfma_f32_32x32x16_bf16 v[50:65], v[200:203], v[208:211], v[50:65]
	v_mfma_f32_32x32x16_bf16 v[34:49], v[200:203], v[212:215], v[34:49]
	s_add_u32 s14, s4, 0xb60080
	s_addc_u32 s15, s5, 0
	s_add_u32 m0, vcc_lo, 0xc000
	v_lshl_add_u64 v[164:165], v[138:139], 0, s[14:15]
	global_load_lds_dwordx4 v[164:165], off
	ds_read_b128 v[200:203], v0 offset:8192
	s_waitcnt lgkmcnt(5)
	v_mfma_f32_32x32x16_bf16 v[18:33], v[204:207], v[208:211], v[18:33]
	v_mfma_f32_32x32x16_bf16 v[2:17], v[204:207], v[212:215], v[2:17]
	s_add_u32 s14, s4, 0xb90080
	s_addc_u32 s15, s5, 0
	s_add_u32 m0, vcc_lo, 0xe000
	v_lshl_add_u64 v[164:165], v[138:139], 0, s[14:15]
	global_load_lds_dwordx4 v[164:165], off
	ds_read_b128 v[204:207], v0 offset:12288
	v_add3_u32 v155, s13, v150, v149
	v_add_u32_e32 v155, v155, v154
	v_add3_u32 v0, s13, v147, v149
	v_add_u32_e32 v0, v0, v154
	ds_read_b128 v[208:211], v155 offset:32768
	ds_read_b128 v[212:215], v155 offset:36864
	s_waitcnt lgkmcnt(5)
	v_mfma_f32_32x32x16_bf16 v[114:129], v[192:195], v[156:159], v[114:129]
	v_mfma_f32_32x32x16_bf16 v[98:113], v[192:195], v[160:163], v[98:113]
	ds_read_b128 v[192:195], v0
	s_waitcnt lgkmcnt(5)
	v_mfma_f32_32x32x16_bf16 v[82:97], v[196:199], v[156:159], v[82:97]
	v_mfma_f32_32x32x16_bf16 v[66:81], v[196:199], v[160:163], v[66:81]
	ds_read_b128 v[196:199], v0 offset:4096
	s_waitcnt lgkmcnt(5)
	v_mfma_f32_32x32x16_bf16 v[50:65], v[200:203], v[156:159], v[50:65]
	v_mfma_f32_32x32x16_bf16 v[34:49], v[200:203], v[160:163], v[34:49]
	ds_read_b128 v[200:203], v0 offset:8192
	s_waitcnt lgkmcnt(5)
	v_mfma_f32_32x32x16_bf16 v[18:33], v[204:207], v[156:159], v[18:33]
	v_mfma_f32_32x32x16_bf16 v[2:17], v[204:207], v[160:163], v[2:17]
	ds_read_b128 v[204:207], v0 offset:12288
	s_waitcnt lgkmcnt(3)
	v_mfma_f32_32x32x16_bf16 v[114:129], v[192:195], v[208:211], v[114:129]
	v_mfma_f32_32x32x16_bf16 v[98:113], v[192:195], v[212:215], v[98:113]
	s_waitcnt lgkmcnt(0)
	s_waitcnt vmcnt(0)
	s_barrier
; template <int EPI, int AMAP, int KOFFMODE, int K>
; __device__ __forceinline__ void gemm_phase(unsigned char* smem, const bf16_t* A, int lda, const bf16_t* Bt, int NT, const EpiArgs& ea) {
;     ...
;             for (int s = 0; s < 4; ++s) {
;                 if (s < 3) {
;                     const int o_ = (((2 * (s + 1)) ^ yz) & 7) * 16;
;                     fb[(s + 1) & 1][0] = *(const bf16x8*)(Bc + o_);
;                     fb[(s + 1) & 1][1] = *(const bf16x8*)(Bc + 32 * 128 + o_);
; #pragma unroll
;                     for (int i = 0; i < 4; ++i) fa[(s + 1) & 1][i] = *(const bf16x8*)(Ac + i * 32 * 128 + o_);
;                 }
; #pragma unroll
;                 for (int i = 0; i < 4; ++i) {
;                     acc[i][0] = __builtin_amdgcn_mfma_f32_32x32x16_bf16(fa[s & 1][i], fb[s & 1][0], acc[i][0], 0, 0, 0);
;                     acc[i][1] = __builtin_amdgcn_mfma_f32_32x32x16_bf16(fa[s & 1][i], fb[s & 1][1], acc[i][1], 0, 0, 0);
;                 }
;                 __builtin_amdgcn_sched_barrier(0);
;             }
;             if (kt + 1 < nk) asm volatile("s_waitcnt vmcnt(0)" ::: "memory");
;             __builtin_amdgcn_s_barrier();
;             cur ^= 1;
	v_add3_u32 v155, s12, v150, v149
	v_add_u32_e32 v155, v155, v151
	v_add3_u32 v0, s12, v147, v149
	v_add_u32_e32 v0, v0, v151
	ds_read_b128 v[156:159], v155 offset:32768
	ds_read_b128 v[160:163], v155 offset:36864
	ds_read_b128 v[192:195], v0
	v_mfma_f32_32x32x16_bf16 v[82:97], v[196:199], v[208:211], v[82:97]
	v_mfma_f32_32x32x16_bf16 v[66:81], v[196:199], v[212:215], v[66:81]
	ds_read_b128 v[196:199], v0 offset:4096
	v_mfma_f32_32x32x16_bf16 v[50:65], v[200:203], v[208:211], v[50:65]
	v_mfma_f32_32x32x16_bf16 v[34:49], v[200:203], v[212:215], v[34:49]
	ds_read_b128 v[200:203], v0 offset:8192
	v_mfma_f32_32x32x16_bf16 v[18:33], v[204:207], v[208:211], v[18:33]
	v_mfma_f32_32x32x16_bf16 v[2:17], v[204:207], v[212:215], v[2:17]
	ds_read_b128 v[204:207], v0 offset:12288
	s_xor_b32 s13, s9, 1
	s_add_u32 s4, s4, 0x80
	s_addc_u32 s5, s5, 0
	s_cmpk_eq_i32 s4, 0xb80
	s_cbranch_scc0 .LBB0_461
	s_waitcnt lgkmcnt(0)
	s_andn2_b64 vcc, exec, s[2:3]
	s_lshl_b32 s2, s13, 16
	s_cbranch_vccnz .LBB0_453
	v_add_u32_e32 v0, s8, v142
	s_xor_b32 s3, s2, 0x10000
	v_mad_i64_i32 v[138:139], s[4:5], v0, s37, v[130:131]
	v_add_u32_e32 v0, s3, v143
	v_add_u32_e32 v136, s7, v142
	v_add_u32_e32 v155, 0x8000, v0
	v_readfirstlane_b32 s3, v0
	v_mad_i64_i32 v[136:137], s[4:5], v136, s37, v[132:133]
	s_mov_b32 m0, s3
	v_readfirstlane_b32 s3, v155
	v_add_u32_e32 v155, 0x2000, v0
	global_load_lds_dwordx4 v[138:139], off
	s_mov_b32 m0, s3
	s_mov_b64 s[4:5], 0x30000
	v_readfirstlane_b32 s3, v155
	v_add_u32_e32 v155, 0xa000, v0
	global_load_lds_dwordx4 v[136:137], off
	v_lshl_add_u64 v[156:157], v[138:139], 0, s[4:5]
	s_mov_b32 m0, s3
	v_readfirstlane_b32 s3, v155
	v_add_u32_e32 v155, 0x4000, v0
	global_load_lds_dwordx4 v[156:157], off
	v_lshl_add_u64 v[156:157], v[136:137], 0, s[4:5]
	s_mov_b32 m0, s3
	s_mov_b64 s[4:5], 0x60000
	v_readfirstlane_b32 s3, v155
	v_add_u32_e32 v155, 0xc000, v0
	global_load_lds_dwordx4 v[156:157], off
	v_lshl_add_u64 v[156:157], v[138:139], 0, s[4:5]
	s_mov_b32 m0, s3
	v_readfirstlane_b32 s3, v155
	v_add_u32_e32 v155, 0x6000, v0
	global_load_lds_dwordx4 v[156:157], off
	v_lshl_add_u64 v[156:157], v[136:137], 0, s[4:5]
	s_mov_b32 m0, s3
	s_mov_b64 s[4:5], 0x90000
	v_readfirstlane_b32 s3, v155
	v_add_u32_e32 v0, 0xe000, v0
	global_load_lds_dwordx4 v[156:157], off
	v_lshl_add_u64 v[138:139], v[138:139], 0, s[4:5]
	s_mov_b32 m0, s3
	v_readfirstlane_b32 s3, v0
	global_load_lds_dwordx4 v[138:139], off
	v_lshl_add_u64 v[136:137], v[136:137], 0, s[4:5]
	s_mov_b32 m0, s3
	s_nop 0
	global_load_lds_dwordx4 v[136:137], off
	s_branch .LBB0_453

; template <int EPI, int AMAP, int KOFFMODE, int K>
; __device__ __forceinline__ void gemm_phase(unsigned char* smem, const bf16_t* A, int lda, const bf16_t* Bt, int NT, const EpiArgs& ea) {
;     ...
;         for (int kt = 0; kt < nk; ++kt) {
;             if (kt + 1 < nk) GEMM_DMA(m0, n0, kt + 1, cur ^ 1);
;             else if (have_next) GEMM_DMA(m0n, n0n, 0, cur ^ 1);
;             const unsigned char* Ac = smem + cur * STGB + (wm * 128 + l31) * 128;
;             const unsigned char* Bc = smem + cur * STGB + 32768 + (wn * 64 + l31) * 128;
;             bf16x8 fa[2][4], fb[2][2];
;             fb[0][0] = *(const bf16x8*)(Bc + (((0) ^ yz) & 7) * 16);
;             fb[0][1] = *(const bf16x8*)(Bc + 32 * 128 + (((0) ^ yz) & 7) * 16);
; #pragma unroll
;             for (int i = 0; i < 4; ++i) fa[0][i] = *(const bf16x8*)(Ac + i * 32 * 128 + (((0) ^ yz) & 7) * 16);
; #pragma unroll
;             for (int s = 0; s < 4; ++s) {
;                 if (s < 3) {
;                     const int o_ = (((2 * (s + 1)) ^ yz) & 7) * 16;
;                     fb[(s + 1) & 1][0] = *(const bf16x8*)(Bc + o_);
;                     fb[(s + 1) & 1][1] = *(const bf16x8*)(Bc + 32 * 128 + o_);
; #pragma unroll
;                     for (int i = 0; i < 4; ++i) fa[(s + 1) & 1][i] = *(const bf16x8*)(Ac + i * 32 * 128 + o_);
;                 }
; #pragma unroll
;                 for (int i = 0; i < 4; ++i) {
;                     acc[i][0] = __builtin_amdgcn_mfma_f32_32x32x16_bf16(fa[s & 1][i], fb[s & 1][0], acc[i][0], 0, 0, 0);
;                     acc[i][1] = __builtin_amdgcn_mfma_f32_32x32x16_bf16(fa[s & 1][i], fb[s & 1][1], acc[i][1], 0, 0, 0);
;                 }
;                 __builtin_amdgcn_sched_barrier(0);
;             }
;             if (kt + 1 < nk) asm volatile("s_waitcnt vmcnt(0)" ::: "memory");
;             __builtin_amdgcn_s_barrier();
;             cur ^= 1;
;         }
.LBB0_927:
	s_lshr_b32 s14, s12, 1
	s_mulk_i32 s14, 0xc0
	s_and_b32 s20, s13, 64
	s_add_i32 s20, s14, s20
	s_mov_b32 s9, s15
	s_lshl_b32 s15, s9, 16
	s_xor_b32 s14, s15, 0x10000
	v_readfirstlane_b32 s28, v143
	s_nop 0
	s_add_u32 s28, s28, s14
	v_add3_u32 v155, s15, v150, v149
	v_add_u32_e32 v155, v155, v152
	v_add3_u32 v0, s15, v147, v149
	v_add_u32_e32 v0, v0, v152
	ds_read_b128 v[208:211], v155 offset:32768
	ds_read_b128 v[212:215], v155 offset:36864
	s_waitcnt lgkmcnt(5)
	v_mfma_f32_32x32x16_bf16 v[114:129], v[192:195], v[156:159], v[114:129]
	s_lshl_b64 s[34:35], s[20:21], 1
	s_mov_b32 m0, s28
	v_lshl_add_u64 v[164:165], v[136:137], 0, s[34:35]
	global_load_lds_dwordx4 v[164:165], off
	v_mfma_f32_32x32x16_bf16 v[98:113], v[192:195], v[160:163], v[98:113]
	s_lshl_b64 s[34:35], s[20:21], 1
	s_add_u32 s34, s34, 0x60000
	s_addc_u32 s35, s35, 0
	s_add_u32 m0, s28, 0x2000
	v_lshl_add_u64 v[164:165], v[136:137], 0, s[34:35]
	global_load_lds_dwordx4 v[164:165], off
	ds_read_b128 v[192:195], v0
	s_waitcnt lgkmcnt(5)
	v_mfma_f32_32x32x16_bf16 v[82:97], v[196:199], v[156:159], v[82:97]
	s_lshl_b64 s[34:35], s[20:21], 1
	s_add_u32 s34, s34, 0xc0000
	s_addc_u32 s35, s35, 0
	s_add_u32 m0, s28, 0x4000
	v_lshl_add_u64 v[164:165], v[136:137], 0, s[34:35]
	global_load_lds_dwordx4 v[164:165], off
	v_mfma_f32_32x32x16_bf16 v[66:81], v[196:199], v[160:163], v[66:81]
	s_lshl_b64 s[34:35], s[20:21], 1
	s_add_u32 s34, s34, 0x120000
	s_addc_u32 s35, s35, 0
	s_add_u32 m0, s28, 0x6000
	v_lshl_add_u64 v[164:165], v[136:137], 0, s[34:35]
	global_load_lds_dwordx4 v[164:165], off
	ds_read_b128 v[196:199], v0 offset:4096
	s_waitcnt lgkmcnt(5)
	v_mfma_f32_32x32x16_bf16 v[50:65], v[200:203], v[156:159], v[50:65]
	v_mfma_f32_32x32x16_bf16 v[34:49], v[200:203], v[160:163], v[34:49]
	ds_read_b128 v[200:203], v0 offset:8192
	s_waitcnt lgkmcnt(5)
	v_mfma_f32_32x32x16_bf16 v[18:33], v[204:207], v[156:159], v[18:33]
	v_mfma_f32_32x32x16_bf16 v[2:17], v[204:207], v[160:163], v[2:17]
	ds_read_b128 v[204:207], v0 offset:12288
	v_add3_u32 v155, s15, v150, v149
	v_add_u32_e32 v155, v155, v153
	v_add3_u32 v0, s15, v147, v149
	v_add_u32_e32 v0, v0, v153
	ds_read_b128 v[156:159], v155 offset:32768
	ds_read_b128 v[160:163], v155 offset:36864
	s_waitcnt lgkmcnt(5)
	v_mfma_f32_32x32x16_bf16 v[114:129], v[192:195], v[208:211], v[114:129]
	v_mfma_f32_32x32x16_bf16 v[98:113], v[192:195], v[212:215], v[98:113]
	s_add_u32 s34, s4, 0x7c0080
	s_addc_u32 s35, s5, 0
	s_add_u32 m0, s28, 0x8000
	v_lshl_add_u64 v[164:165], v[138:139], 0, s[34:35]
	global_load_lds_dwordx4 v[164:165], off
	ds_read_b128 v[192:195], v0
	s_waitcnt lgkmcnt(5)
	v_mfma_f32_32x32x16_bf16 v[82:97], v[196:199], v[208:211], v[82:97]
	v_mfma_f32_32x32x16_bf16 v[66:81], v[196:199], v[212:215], v[66:81]
	s_add_u32 s34, s4, s68
	s_addc_u32 s35, s5, s69
	s_add_u32 m0, s28, 0xa000
	v_lshl_add_u64 v[164:165], v[138:139], 0, s[34:35]
	global_load_lds_dwordx4 v[164:165], off
	ds_read_b128 v[196:199], v0 offset:4096
	s_waitcnt lgkmcnt(5)
	v_mfma_f32_32x32x16_bf16 v[50:65], v[200:203], v[208:211], v[50:65]
	v_mfma_f32_32x32x16_bf16 v[34:49], v[200:203], v[212:215], v[34:49]
	s_add_u32 s34, s4, s80
	s_addc_u32 s35, s5, s81
	s_add_u32 m0, s28, 0xc000
	v_lshl_add_u64 v[164:165], v[138:139], 0, s[34:35]
	global_load_lds_dwordx4 v[164:165], off
	ds_read_b128 v[200:203], v0 offset:8192
	s_waitcnt lgkmcnt(5)
	v_mfma_f32_32x32x16_bf16 v[18:33], v[204:207], v[208:211], v[18:33]
	v_mfma_f32_32x32x16_bf16 v[2:17], v[204:207], v[212:215], v[2:17]
	s_add_u32 s34, s4, 0x880080
	s_addc_u32 s35, s5, 0
	s_add_u32 m0, s28, 0xe000
	v_lshl_add_u64 v[164:165], v[138:139], 0, s[34:35]
	global_load_lds_dwordx4 v[164:165], off
	ds_read_b128 v[204:207], v0 offset:12288
	v_add3_u32 v155, s15, v150, v149
	v_add_u32_e32 v155, v155, v154
	v_add3_u32 v0, s15, v147, v149
	v_add_u32_e32 v0, v0, v154
	ds_read_b128 v[208:211], v155 offset:32768
	ds_read_b128 v[212:215], v155 offset:36864
	s_waitcnt lgkmcnt(5)
	v_mfma_f32_32x32x16_bf16 v[114:129], v[192:195], v[156:159], v[114:129]
	v_mfma_f32_32x32x16_bf16 v[98:113], v[192:195], v[160:163], v[98:113]
	ds_read_b128 v[192:195], v0
	s_waitcnt lgkmcnt(5)
	v_mfma_f32_32x32x16_bf16 v[82:97], v[196:199], v[156:159], v[82:97]
	v_mfma_f32_32x32x16_bf16 v[66:81], v[196:199], v[160:163], v[66:81]
	ds_read_b128 v[196:199], v0 offset:4096
	s_waitcnt lgkmcnt(5)
	v_mfma_f32_32x32x16_bf16 v[50:65], v[200:203], v[156:159], v[50:65]
	v_mfma_f32_32x32x16_bf16 v[34:49], v[200:203], v[160:163], v[34:49]
	ds_read_b128 v[200:203], v0 offset:8192
	s_waitcnt lgkmcnt(5)
	v_mfma_f32_32x32x16_bf16 v[18:33], v[204:207], v[156:159], v[18:33]
	v_mfma_f32_32x32x16_bf16 v[2:17], v[204:207], v[160:163], v[2:17]
	ds_read_b128 v[204:207], v0 offset:12288
	s_waitcnt lgkmcnt(3)
	v_mfma_f32_32x32x16_bf16 v[114:129], v[192:195], v[208:211], v[114:129]
	v_mfma_f32_32x32x16_bf16 v[98:113], v[192:195], v[212:215], v[98:113]
	s_waitcnt lgkmcnt(0)
	s_waitcnt vmcnt(0)
	s_barrier
; template <int EPI, int AMAP, int KOFFMODE, int K>
; __device__ __forceinline__ void gemm_phase(unsigned char* smem, const bf16_t* A, int lda, const bf16_t* Bt, int NT, const EpiArgs& ea) {
;     ...
;             for (int s = 0; s < 4; ++s) {
;                 if (s < 3) {
;                     const int o_ = (((2 * (s + 1)) ^ yz) & 7) * 16;
;                     fb[(s + 1) & 1][0] = *(const bf16x8*)(Bc + o_);
;                     fb[(s + 1) & 1][1] = *(const bf16x8*)(Bc + 32 * 128 + o_);
; #pragma unroll
;                     for (int i = 0; i < 4; ++i) fa[(s + 1) & 1][i] = *(const bf16x8*)(Ac + i * 32 * 128 + o_);
;                 }
; #pragma unroll
;                 for (int i = 0; i < 4; ++i) {
;                     acc[i][0] = __builtin_amdgcn_mfma_f32_32x32x16_bf16(fa[s & 1][i], fb[s & 1][0], acc[i][0], 0, 0, 0);
;                     acc[i][1] = __builtin_amdgcn_mfma_f32_32x32x16_bf16(fa[s & 1][i], fb[s & 1][1], acc[i][1], 0, 0, 0);
;                 }
;                 __builtin_amdgcn_sched_barrier(0);
;             }
;             if (kt + 1 < nk) asm volatile("s_waitcnt vmcnt(0)" ::: "memory");
;             __builtin_amdgcn_s_barrier();
;             cur ^= 1;
	v_add3_u32 v155, s14, v150, v149
	v_add_u32_e32 v155, v155, v151
	v_add3_u32 v0, s14, v147, v149
	v_add_u32_e32 v0, v0, v151
	ds_read_b128 v[156:159], v155 offset:32768
	ds_read_b128 v[160:163], v155 offset:36864
	ds_read_b128 v[192:195], v0
	v_mfma_f32_32x32x16_bf16 v[82:97], v[196:199], v[208:211], v[82:97]
	v_mfma_f32_32x32x16_bf16 v[66:81], v[196:199], v[212:215], v[66:81]
	ds_read_b128 v[196:199], v0 offset:4096
	v_mfma_f32_32x32x16_bf16 v[50:65], v[200:203], v[208:211], v[50:65]
	v_mfma_f32_32x32x16_bf16 v[34:49], v[200:203], v[212:215], v[34:49]
	ds_read_b128 v[200:203], v0 offset:8192
	v_mfma_f32_32x32x16_bf16 v[18:33], v[204:207], v[208:211], v[18:33]
	v_mfma_f32_32x32x16_bf16 v[2:17], v[204:207], v[212:215], v[2:17]
	ds_read_b128 v[204:207], v0 offset:12288
	s_xor_b32 s15, s9, 1
	s_add_u32 s4, s4, 0x80
	s_addc_u32 s5, s5, 0
	s_add_i32 s12, s12, 1
	s_add_i32 s13, s13, 64
	s_mov_b64 s[34:35], 0x60000
	s_cmpk_eq_i32 s4, 0xf80
	s_cbranch_scc0 .LBB0_927
	s_waitcnt lgkmcnt(0)
	v_writelane_b32 v251, s20, 18
	s_andn2_b64 vcc, exec, s[2:3]
	s_lshl_b32 s2, s15, 16
	v_writelane_b32 v251, s21, 19
	s_cbranch_vccnz .LBB0_919
	v_add_u32_e32 v0, s8, v142
	s_movk_i32 s3, 0x1800
	v_mad_i64_i32 v[138:139], s[4:5], v0, s3, v[130:131]
	s_xor_b32 s3, s2, 0x10000
	v_add_u32_e32 v136, s7, v142
	v_add_u32_e32 v0, s3, v143
	v_ashrrev_i32_e32 v137, 31, v136
	v_add_u32_e32 v155, 0x8000, v0
	v_readfirstlane_b32 s3, v0
	v_lshlrev_b64 v[136:137], 12, v[136:137]
	s_mov_b32 m0, s3
	v_readfirstlane_b32 s3, v155
	v_add_u32_e32 v155, 0x2000, v0
	v_lshl_add_u64 v[136:137], v[132:133], 0, v[136:137]
	global_load_lds_dwordx4 v[138:139], off
	s_mov_b32 m0, s3
	v_readfirstlane_b32 s3, v155
	v_add_u32_e32 v155, 0xa000, v0
	global_load_lds_dwordx4 v[136:137], off
	v_lshl_add_u64 v[156:157], v[138:139], 0, s[34:35]
	s_mov_b32 m0, s3
	s_mov_b64 s[4:5], 0x40000
	v_readfirstlane_b32 s3, v155
	v_add_u32_e32 v155, 0x4000, v0
	global_load_lds_dwordx4 v[156:157], off
	v_lshl_add_u64 v[156:157], v[136:137], 0, s[4:5]
	s_mov_b32 m0, s3
	s_mov_b64 s[4:5], 0xc0000
	v_readfirstlane_b32 s3, v155
	v_add_u32_e32 v155, 0xc000, v0
	global_load_lds_dwordx4 v[156:157], off
	v_lshl_add_u64 v[156:157], v[138:139], 0, s[4:5]
	s_mov_b32 m0, s3
	s_mov_b64 s[12:13], 0x80000
	v_readfirstlane_b32 s3, v155
	v_add_u32_e32 v155, 0x6000, v0
	global_load_lds_dwordx4 v[156:157], off
	v_lshl_add_u64 v[156:157], v[136:137], 0, s[12:13]
	s_mov_b32 m0, s3
	s_mov_b64 s[12:13], 0x120000
	v_readfirstlane_b32 s3, v155
	v_add_u32_e32 v0, 0xe000, v0
	global_load_lds_dwordx4 v[156:157], off
	v_lshl_add_u64 v[138:139], v[138:139], 0, s[12:13]
	s_mov_b32 m0, s3
	v_readfirstlane_b32 s3, v0
	global_load_lds_dwordx4 v[138:139], off
	v_lshl_add_u64 v[136:137], v[136:137], 0, s[4:5]
	s_mov_b32 m0, s3
	s_nop 0
	global_load_lds_dwordx4 v[136:137], off
	s_branch .LBB0_919

; template <int EPI, int AMAP, int KOFFMODE, int K>
; __device__ __forceinline__ void gemm_phase(unsigned char* smem, const bf16_t* A, int lda, const bf16_t* Bt, int NT, const EpiArgs& ea) {
;     ...
;         for (int kt = 0; kt < nk; ++kt) {
;             if (kt + 1 < nk) GEMM_DMA(m0, n0, kt + 1, cur ^ 1);
;             else if (have_next) GEMM_DMA(m0n, n0n, 0, cur ^ 1);
;             const unsigned char* Ac = smem + cur * STGB + (wm * 128 + l31) * 128;
;             const unsigned char* Bc = smem + cur * STGB + 32768 + (wn * 64 + l31) * 128;
;             bf16x8 fa[2][4], fb[2][2];
;             fb[0][0] = *(const bf16x8*)(Bc + (((0) ^ yz) & 7) * 16);
;             fb[0][1] = *(const bf16x8*)(Bc + 32 * 128 + (((0) ^ yz) & 7) * 16);
; #pragma unroll
;             for (int i = 0; i < 4; ++i) fa[0][i] = *(const bf16x8*)(Ac + i * 32 * 128 + (((0) ^ yz) & 7) * 16);
; #pragma unroll
;             for (int s = 0; s < 4; ++s) {
;                 if (s < 3) {
;                     const int o_ = (((2 * (s + 1)) ^ yz) & 7) * 16;
;                     fb[(s + 1) & 1][0] = *(const bf16x8*)(Bc + o_);
;                     fb[(s + 1) & 1][1] = *(const bf16x8*)(Bc + 32 * 128 + o_);
; #pragma unroll
;                     for (int i = 0; i < 4; ++i) fa[(s + 1) & 1][i] = *(const bf16x8*)(Ac + i * 32 * 128 + o_);
;                 }
; #pragma unroll
;                 for (int i = 0; i < 4; ++i) {
;                     acc[i][0] = __builtin_amdgcn_mfma_f32_32x32x16_bf16(fa[s & 1][i], fb[s & 1][0], acc[i][0], 0, 0, 0);
;                     acc[i][1] = __builtin_amdgcn_mfma_f32_32x32x16_bf16(fa[s & 1][i], fb[s & 1][1], acc[i][1], 0, 0, 0);
;                 }
;                 __builtin_amdgcn_sched_barrier(0);
;             }
;             if (kt + 1 < nk) asm volatile("s_waitcnt vmcnt(0)" ::: "memory");
;             __builtin_amdgcn_s_barrier();
;             cur ^= 1;
;         }
.LBB0_1032:
	s_mov_b32 s11, s15
	s_lshl_b32 s15, s11, 16
	s_xor_b32 s14, s15, 0x10000
	v_readfirstlane_b32 s28, v144
	s_nop 0
	s_add_u32 s28, s28, s14
	v_add3_u32 v191, s15, v151, v150
	v_add_u32_e32 v191, v191, v153
	v_add3_u32 v0, s15, v149, v150
	v_add_u32_e32 v0, v0, v153
	ds_read_b128 v[208:211], v191 offset:32768
	ds_read_b128 v[212:215], v191 offset:36864
	s_waitcnt lgkmcnt(5)
	v_mfma_f32_32x32x16_bf16 v[114:129], v[192:195], v[156:159], v[114:129]
	s_add_u32 s34, s4, s20
	s_addc_u32 s35, s5, s21
	s_mov_b32 m0, s28
	v_lshl_add_u64 v[164:165], v[136:137], 0, s[34:35]
	global_load_lds_dwordx4 v[164:165], off
	v_mfma_f32_32x32x16_bf16 v[98:113], v[192:195], v[160:163], v[98:113]
	s_add_u32 s34, s4, vcc_lo
	s_addc_u32 s35, s5, vcc_hi
	s_add_u32 m0, s28, 0x2000
	v_lshl_add_u64 v[164:165], v[136:137], 0, s[34:35]
	global_load_lds_dwordx4 v[164:165], off
	ds_read_b128 v[192:195], v0
	s_waitcnt lgkmcnt(5)
	v_mfma_f32_32x32x16_bf16 v[82:97], v[196:199], v[156:159], v[82:97]
	s_add_u32 s34, s4, s68
	s_addc_u32 s35, s5, s69
	s_add_u32 m0, s28, 0x4000
	v_lshl_add_u64 v[164:165], v[136:137], 0, s[34:35]
	global_load_lds_dwordx4 v[164:165], off
	v_mfma_f32_32x32x16_bf16 v[66:81], v[196:199], v[160:163], v[66:81]
	s_add_u32 s34, s4, s88
	s_addc_u32 s35, s5, s89
	s_add_u32 m0, s28, 0x6000
	v_lshl_add_u64 v[164:165], v[136:137], 0, s[34:35]
	global_load_lds_dwordx4 v[164:165], off
	ds_read_b128 v[196:199], v0 offset:4096
	s_waitcnt lgkmcnt(5)
	v_mfma_f32_32x32x16_bf16 v[50:65], v[200:203], v[156:159], v[50:65]
	v_mfma_f32_32x32x16_bf16 v[34:49], v[200:203], v[160:163], v[34:49]
	ds_read_b128 v[200:203], v0 offset:8192
	s_waitcnt lgkmcnt(5)
	v_mfma_f32_32x32x16_bf16 v[18:33], v[204:207], v[156:159], v[18:33]
	v_mfma_f32_32x32x16_bf16 v[2:17], v[204:207], v[160:163], v[2:17]
	ds_read_b128 v[204:207], v0 offset:12288
	v_add3_u32 v191, s15, v151, v150
	v_add_u32_e32 v191, v191, v154
	v_add3_u32 v0, s15, v149, v150
	v_add_u32_e32 v0, v0, v154
	ds_read_b128 v[156:159], v191 offset:32768
	ds_read_b128 v[160:163], v191 offset:36864
	s_waitcnt lgkmcnt(5)
	v_mfma_f32_32x32x16_bf16 v[114:129], v[192:195], v[208:211], v[114:129]
	v_mfma_f32_32x32x16_bf16 v[98:113], v[192:195], v[212:215], v[98:113]
	s_add_u32 s34, s4, 0xe00080
	s_addc_u32 s35, s5, 0
	s_add_u32 m0, s28, 0x8000
	v_lshl_add_u64 v[164:165], v[138:139], 0, s[34:35]
	global_load_lds_dwordx4 v[164:165], off
	ds_read_b128 v[192:195], v0
	s_waitcnt lgkmcnt(5)
	v_mfma_f32_32x32x16_bf16 v[82:97], v[196:199], v[208:211], v[82:97]
	v_mfma_f32_32x32x16_bf16 v[66:81], v[196:199], v[212:215], v[66:81]
	s_add_u32 s34, s4, 0xe20080
	s_addc_u32 s35, s5, 0
	s_add_u32 m0, s28, 0xa000
	v_lshl_add_u64 v[164:165], v[138:139], 0, s[34:35]
	global_load_lds_dwordx4 v[164:165], off
	ds_read_b128 v[196:199], v0 offset:4096
	s_waitcnt lgkmcnt(5)
	v_mfma_f32_32x32x16_bf16 v[50:65], v[200:203], v[208:211], v[50:65]
	v_mfma_f32_32x32x16_bf16 v[34:49], v[200:203], v[212:215], v[34:49]
	s_add_u32 s34, s4, 0xe40080
	s_addc_u32 s35, s5, 0
	s_add_u32 m0, s28, 0xc000
	v_lshl_add_u64 v[164:165], v[138:139], 0, s[34:35]
	global_load_lds_dwordx4 v[164:165], off
	ds_read_b128 v[200:203], v0 offset:8192
	s_waitcnt lgkmcnt(5)
	v_mfma_f32_32x32x16_bf16 v[18:33], v[204:207], v[208:211], v[18:33]
	v_mfma_f32_32x32x16_bf16 v[2:17], v[204:207], v[212:215], v[2:17]
	s_add_u32 s34, s4, 0xe60080
	s_addc_u32 s35, s5, 0
	s_add_u32 m0, s28, 0xe000
	v_lshl_add_u64 v[164:165], v[138:139], 0, s[34:35]
	global_load_lds_dwordx4 v[164:165], off
	ds_read_b128 v[204:207], v0 offset:12288
	v_add3_u32 v191, s15, v151, v150
	v_add_u32_e32 v191, v191, v155
	v_add3_u32 v0, s15, v149, v150
	v_add_u32_e32 v0, v0, v155
	ds_read_b128 v[208:211], v191 offset:32768
	ds_read_b128 v[212:215], v191 offset:36864
	s_waitcnt lgkmcnt(5)
	v_mfma_f32_32x32x16_bf16 v[114:129], v[192:195], v[156:159], v[114:129]
	v_mfma_f32_32x32x16_bf16 v[98:113], v[192:195], v[160:163], v[98:113]
	ds_read_b128 v[192:195], v0
	s_waitcnt lgkmcnt(5)
	v_mfma_f32_32x32x16_bf16 v[82:97], v[196:199], v[156:159], v[82:97]
	v_mfma_f32_32x32x16_bf16 v[66:81], v[196:199], v[160:163], v[66:81]
	ds_read_b128 v[196:199], v0 offset:4096
	s_waitcnt lgkmcnt(5)
	v_mfma_f32_32x32x16_bf16 v[50:65], v[200:203], v[156:159], v[50:65]
	v_mfma_f32_32x32x16_bf16 v[34:49], v[200:203], v[160:163], v[34:49]
	ds_read_b128 v[200:203], v0 offset:8192
	s_waitcnt lgkmcnt(5)
	v_mfma_f32_32x32x16_bf16 v[18:33], v[204:207], v[156:159], v[18:33]
	v_mfma_f32_32x32x16_bf16 v[2:17], v[204:207], v[160:163], v[2:17]
	ds_read_b128 v[204:207], v0 offset:12288
	s_waitcnt lgkmcnt(3)
	v_mfma_f32_32x32x16_bf16 v[114:129], v[192:195], v[208:211], v[114:129]
	v_mfma_f32_32x32x16_bf16 v[98:113], v[192:195], v[212:215], v[98:113]
	s_waitcnt lgkmcnt(0)
	s_waitcnt vmcnt(0)
	s_barrier
; template <int EPI, int AMAP, int KOFFMODE, int K>
; __device__ __forceinline__ void gemm_phase(unsigned char* smem, const bf16_t* A, int lda, const bf16_t* Bt, int NT, const EpiArgs& ea) {
;     ...
;             for (int s = 0; s < 4; ++s) {
;                 if (s < 3) {
;                     const int o_ = (((2 * (s + 1)) ^ yz) & 7) * 16;
;                     fb[(s + 1) & 1][0] = *(const bf16x8*)(Bc + o_);
;                     fb[(s + 1) & 1][1] = *(const bf16x8*)(Bc + 32 * 128 + o_);
; #pragma unroll
;                     for (int i = 0; i < 4; ++i) fa[(s + 1) & 1][i] = *(const bf16x8*)(Ac + i * 32 * 128 + o_);
;                 }
; #pragma unroll
;                 for (int i = 0; i < 4; ++i) {
;                     acc[i][0] = __builtin_amdgcn_mfma_f32_32x32x16_bf16(fa[s & 1][i], fb[s & 1][0], acc[i][0], 0, 0, 0);
;                     acc[i][1] = __builtin_amdgcn_mfma_f32_32x32x16_bf16(fa[s & 1][i], fb[s & 1][1], acc[i][1], 0, 0, 0);
;                 }
;                 __builtin_amdgcn_sched_barrier(0);
;             }
;             if (kt + 1 < nk) asm volatile("s_waitcnt vmcnt(0)" ::: "memory");
;             __builtin_amdgcn_s_barrier();
;             cur ^= 1;
	v_add3_u32 v191, s14, v151, v150
	v_add_u32_e32 v191, v191, v152
	v_add3_u32 v0, s14, v149, v150
	v_add_u32_e32 v0, v0, v152
	ds_read_b128 v[156:159], v191 offset:32768
	ds_read_b128 v[160:163], v191 offset:36864
	ds_read_b128 v[192:195], v0
	v_mfma_f32_32x32x16_bf16 v[82:97], v[196:199], v[208:211], v[82:97]
	v_mfma_f32_32x32x16_bf16 v[66:81], v[196:199], v[212:215], v[66:81]
	ds_read_b128 v[196:199], v0 offset:4096
	v_mfma_f32_32x32x16_bf16 v[50:65], v[200:203], v[208:211], v[50:65]
	v_mfma_f32_32x32x16_bf16 v[34:49], v[200:203], v[212:215], v[34:49]
	ds_read_b128 v[200:203], v0 offset:8192
	v_mfma_f32_32x32x16_bf16 v[18:33], v[204:207], v[208:211], v[18:33]
	v_mfma_f32_32x32x16_bf16 v[2:17], v[204:207], v[212:215], v[2:17]
	ds_read_b128 v[204:207], v0 offset:12288
	s_xor_b32 s15, s11, 1
	s_add_u32 s4, s4, 0x80
	s_addc_u32 s5, s5, 0
	s_cmpk_eq_i32 s4, 0x780
	s_cbranch_scc0 .LBB0_1032
	s_waitcnt lgkmcnt(0)
	s_andn2_b64 vcc, exec, s[2:3]
	s_lshl_b32 s2, s15, 16
	s_cbranch_vccnz .LBB0_1024
	v_add_u32_e32 v136, s10, v143
	s_xor_b32 s3, s2, 0x10000
	v_ashrrev_i32_e32 v137, 31, v136
	v_add_u32_e32 v138, s9, v143
	v_add_u32_e32 v0, s3, v144
	v_lshlrev_b64 v[136:137], 11, v[136:137]
	v_ashrrev_i32_e32 v139, 31, v138
	v_add_u32_e32 v156, 0x8000, v0
	v_readfirstlane_b32 s3, v0
	v_lshlrev_b64 v[138:139], 11, v[138:139]
	v_lshl_add_u64 v[136:137], v[130:131], 0, v[136:137]
	s_mov_b32 m0, s3
	v_readfirstlane_b32 s3, v156
	v_add_u32_e32 v158, 0x2000, v0
	v_lshl_add_u64 v[138:139], v[132:133], 0, v[138:139]
	global_load_lds_dwordx4 v[136:137], off
	s_mov_b32 m0, s3
	s_mov_b64 s[4:5], 0x20000
	v_readfirstlane_b32 s3, v158
	v_add_u32_e32 v158, 0xa000, v0
	global_load_lds_dwordx4 v[138:139], off
	v_lshl_add_u64 v[156:157], v[136:137], 0, s[4:5]
	s_mov_b32 m0, s3
	v_readfirstlane_b32 s3, v158
	v_add_u32_e32 v158, 0x4000, v0
	global_load_lds_dwordx4 v[156:157], off
	v_lshl_add_u64 v[156:157], v[138:139], 0, s[4:5]
	s_mov_b32 m0, s3
	s_mov_b64 s[4:5], 0x40000
	v_readfirstlane_b32 s3, v158
	v_add_u32_e32 v158, 0xc000, v0
	global_load_lds_dwordx4 v[156:157], off
	v_lshl_add_u64 v[156:157], v[136:137], 0, s[4:5]
	s_mov_b32 m0, s3
	v_readfirstlane_b32 s3, v158
	global_load_lds_dwordx4 v[156:157], off
	v_lshl_add_u64 v[156:157], v[138:139], 0, s[4:5]
	s_mov_b32 m0, s3
	s_mov_b64 s[4:5], 0x60000
	global_load_lds_dwordx4 v[156:157], off
	v_add_u32_e32 v156, 0x6000, v0
	v_add_u32_e32 v0, 0xe000, v0
	v_readfirstlane_b32 s3, v156
	v_lshl_add_u64 v[136:137], v[136:137], 0, s[4:5]
	s_mov_b32 m0, s3
	v_readfirstlane_b32 s3, v0
	global_load_lds_dwordx4 v[136:137], off
	v_lshl_add_u64 v[136:137], v[138:139], 0, s[4:5]
	s_mov_b32 m0, s3
	s_nop 0
	global_load_lds_dwordx4 v[136:137], off
	s_branch .LBB0_1024

; template <int EPI, int AMAP, int KOFFMODE, int K>
; __device__ __forceinline__ void gemm_phase(unsigned char* smem, const bf16_t* A, int lda, const bf16_t* Bt, int NT, const EpiArgs& ea) {
;     ...
;         for (int kt = 0; kt < nk; ++kt) {
;             if (kt + 1 < nk) GEMM_DMA(m0, n0, kt + 1, cur ^ 1);
;             else if (have_next) GEMM_DMA(m0n, n0n, 0, cur ^ 1);
;             const unsigned char* Ac = smem + cur * STGB + (wm * 128 + l31) * 128;
;             const unsigned char* Bc = smem + cur * STGB + 32768 + (wn * 64 + l31) * 128;
;             bf16x8 fa[2][4], fb[2][2];
;             fb[0][0] = *(const bf16x8*)(Bc + (((0) ^ yz) & 7) * 16);
;             fb[0][1] = *(const bf16x8*)(Bc + 32 * 128 + (((0) ^ yz) & 7) * 16);
; #pragma unroll
;             for (int i = 0; i < 4; ++i) fa[0][i] = *(const bf16x8*)(Ac + i * 32 * 128 + (((0) ^ yz) & 7) * 16);
; #pragma unroll
;             for (int s = 0; s < 4; ++s) {
;                 if (s < 3) {
;                     const int o_ = (((2 * (s + 1)) ^ yz) & 7) * 16;
;                     fb[(s + 1) & 1][0] = *(const bf16x8*)(Bc + o_);
;                     fb[(s + 1) & 1][1] = *(const bf16x8*)(Bc + 32 * 128 + o_);
; #pragma unroll
;                     for (int i = 0; i < 4; ++i) fa[(s + 1) & 1][i] = *(const bf16x8*)(Ac + i * 32 * 128 + o_);
;                 }
; #pragma unroll
;                 for (int i = 0; i < 4; ++i) {
;                     acc[i][0] = __builtin_amdgcn_mfma_f32_32x32x16_bf16(fa[s & 1][i], fb[s & 1][0], acc[i][0], 0, 0, 0);
;                     acc[i][1] = __builtin_amdgcn_mfma_f32_32x32x16_bf16(fa[s & 1][i], fb[s & 1][1], acc[i][1], 0, 0, 0);
;                 }
;                 __builtin_amdgcn_sched_barrier(0);
;             }
;             if (kt + 1 < nk) asm volatile("s_waitcnt vmcnt(0)" ::: "memory");
;             __builtin_amdgcn_s_barrier();
;             cur ^= 1;
;         }
.LBB0_1161:
	s_mov_b32 s13, s34
	s_lshl_b32 s36, s13, 16
	s_xor_b32 s28, s36, 0x10000
	v_readfirstlane_b32 vcc_lo, v144
	s_nop 0
	s_add_u32 vcc_lo, vcc_lo, s28
	v_add3_u32 v191, s36, v151, v150
	v_add_u32_e32 v191, v191, v153
	v_add3_u32 v0, s36, v149, v150
	v_add_u32_e32 v0, v0, v153
	ds_read_b128 v[208:211], v191 offset:32768
	ds_read_b128 v[212:215], v191 offset:36864
	s_waitcnt lgkmcnt(5)
	v_mfma_f32_32x32x16_bf16 v[114:129], v[192:195], v[156:159], v[114:129]
	s_add_u32 s34, s8, 0x4100080
	s_addc_u32 s35, s9, 0
	s_mov_b32 m0, vcc_lo
	v_lshl_add_u64 v[164:165], v[136:137], 0, s[34:35]
	global_load_lds_dwordx4 v[164:165], off
	v_mfma_f32_32x32x16_bf16 v[98:113], v[192:195], v[160:163], v[98:113]
	s_add_u32 s34, s8, 0x4158080
	s_addc_u32 s35, s9, 0
	s_add_u32 m0, vcc_lo, 0x2000
	v_lshl_add_u64 v[164:165], v[136:137], 0, s[34:35]
	global_load_lds_dwordx4 v[164:165], off
	ds_read_b128 v[192:195], v0
	s_waitcnt lgkmcnt(5)
	v_mfma_f32_32x32x16_bf16 v[82:97], v[196:199], v[156:159], v[82:97]
	s_add_u32 s34, s8, 0x41b0080
	s_addc_u32 s35, s9, 0
	s_add_u32 m0, vcc_lo, 0x4000
	v_lshl_add_u64 v[164:165], v[136:137], 0, s[34:35]
	global_load_lds_dwordx4 v[164:165], off
	v_mfma_f32_32x32x16_bf16 v[66:81], v[196:199], v[160:163], v[66:81]
	s_add_u32 s34, s8, 0x4208080
	s_addc_u32 s35, s9, 0
	s_add_u32 m0, vcc_lo, 0x6000
	v_lshl_add_u64 v[164:165], v[136:137], 0, s[34:35]
	global_load_lds_dwordx4 v[164:165], off
	ds_read_b128 v[196:199], v0 offset:4096
	s_waitcnt lgkmcnt(5)
	v_mfma_f32_32x32x16_bf16 v[50:65], v[200:203], v[156:159], v[50:65]
	v_mfma_f32_32x32x16_bf16 v[34:49], v[200:203], v[160:163], v[34:49]
	ds_read_b128 v[200:203], v0 offset:8192
	s_waitcnt lgkmcnt(5)
	v_mfma_f32_32x32x16_bf16 v[18:33], v[204:207], v[156:159], v[18:33]
	v_mfma_f32_32x32x16_bf16 v[2:17], v[204:207], v[160:163], v[2:17]
	ds_read_b128 v[204:207], v0 offset:12288
	v_add3_u32 v191, s36, v151, v150
	v_add_u32_e32 v191, v191, v154
	v_add3_u32 v0, s36, v149, v150
	v_add_u32_e32 v0, v0, v154
	ds_read_b128 v[156:159], v191 offset:32768
	ds_read_b128 v[160:163], v191 offset:36864
	s_waitcnt lgkmcnt(5)
	v_mfma_f32_32x32x16_bf16 v[114:129], v[192:195], v[208:211], v[114:129]
	v_mfma_f32_32x32x16_bf16 v[98:113], v[192:195], v[212:215], v[98:113]
	s_add_u32 s34, s8, 0x1900080
	s_addc_u32 s35, s9, 0
	s_add_u32 m0, vcc_lo, 0x8000
	v_lshl_add_u64 v[164:165], v[138:139], 0, s[34:35]
	global_load_lds_dwordx4 v[164:165], off
	ds_read_b128 v[192:195], v0
	s_waitcnt lgkmcnt(5)
	v_mfma_f32_32x32x16_bf16 v[82:97], v[196:199], v[208:211], v[82:97]
	v_mfma_f32_32x32x16_bf16 v[66:81], v[196:199], v[212:215], v[66:81]
	s_add_u32 s34, s8, 0x1958080
	s_addc_u32 s35, s9, 0
	s_add_u32 m0, vcc_lo, 0xa000
	v_lshl_add_u64 v[164:165], v[138:139], 0, s[34:35]
	global_load_lds_dwordx4 v[164:165], off
	ds_read_b128 v[196:199], v0 offset:4096
	s_waitcnt lgkmcnt(5)
	v_mfma_f32_32x32x16_bf16 v[50:65], v[200:203], v[208:211], v[50:65]
	v_mfma_f32_32x32x16_bf16 v[34:49], v[200:203], v[212:215], v[34:49]
	s_add_u32 s34, s8, 0x19b0080
	s_addc_u32 s35, s9, 0
	s_add_u32 m0, vcc_lo, 0xc000
	v_lshl_add_u64 v[164:165], v[138:139], 0, s[34:35]
	global_load_lds_dwordx4 v[164:165], off
	ds_read_b128 v[200:203], v0 offset:8192
	s_waitcnt lgkmcnt(5)
	v_mfma_f32_32x32x16_bf16 v[18:33], v[204:207], v[208:211], v[18:33]
	v_mfma_f32_32x32x16_bf16 v[2:17], v[204:207], v[212:215], v[2:17]
	s_add_u32 s34, s8, 0x1a08080
	s_addc_u32 s35, s9, 0
	s_add_u32 m0, vcc_lo, 0xe000
	v_lshl_add_u64 v[164:165], v[138:139], 0, s[34:35]
	global_load_lds_dwordx4 v[164:165], off
	ds_read_b128 v[204:207], v0 offset:12288
	v_add3_u32 v191, s36, v151, v150
	v_add_u32_e32 v191, v191, v155
	v_add3_u32 v0, s36, v149, v150
	v_add_u32_e32 v0, v0, v155
	ds_read_b128 v[208:211], v191 offset:32768
	ds_read_b128 v[212:215], v191 offset:36864
	s_waitcnt lgkmcnt(5)
	v_mfma_f32_32x32x16_bf16 v[114:129], v[192:195], v[156:159], v[114:129]
	v_mfma_f32_32x32x16_bf16 v[98:113], v[192:195], v[160:163], v[98:113]
	ds_read_b128 v[192:195], v0
	s_waitcnt lgkmcnt(5)
	v_mfma_f32_32x32x16_bf16 v[82:97], v[196:199], v[156:159], v[82:97]
	v_mfma_f32_32x32x16_bf16 v[66:81], v[196:199], v[160:163], v[66:81]
	ds_read_b128 v[196:199], v0 offset:4096
	s_waitcnt lgkmcnt(5)
	v_mfma_f32_32x32x16_bf16 v[50:65], v[200:203], v[156:159], v[50:65]
	v_mfma_f32_32x32x16_bf16 v[34:49], v[200:203], v[160:163], v[34:49]
	ds_read_b128 v[200:203], v0 offset:8192
	s_waitcnt lgkmcnt(5)
	v_mfma_f32_32x32x16_bf16 v[18:33], v[204:207], v[156:159], v[18:33]
	v_mfma_f32_32x32x16_bf16 v[2:17], v[204:207], v[160:163], v[2:17]
	ds_read_b128 v[204:207], v0 offset:12288
	s_waitcnt lgkmcnt(3)
	v_mfma_f32_32x32x16_bf16 v[114:129], v[192:195], v[208:211], v[114:129]
	v_mfma_f32_32x32x16_bf16 v[98:113], v[192:195], v[212:215], v[98:113]
	s_waitcnt lgkmcnt(0)
	s_waitcnt vmcnt(0)
	s_barrier
; template <int EPI, int AMAP, int KOFFMODE, int K>
; __device__ __forceinline__ void gemm_phase(unsigned char* smem, const bf16_t* A, int lda, const bf16_t* Bt, int NT, const EpiArgs& ea) {
;     ...
;             for (int s = 0; s < 4; ++s) {
;                 if (s < 3) {
;                     const int o_ = (((2 * (s + 1)) ^ yz) & 7) * 16;
;                     fb[(s + 1) & 1][0] = *(const bf16x8*)(Bc + o_);
;                     fb[(s + 1) & 1][1] = *(const bf16x8*)(Bc + 32 * 128 + o_);
; #pragma unroll
;                     for (int i = 0; i < 4; ++i) fa[(s + 1) & 1][i] = *(const bf16x8*)(Ac + i * 32 * 128 + o_);
;                 }
; #pragma unroll
;                 for (int i = 0; i < 4; ++i) {
;                     acc[i][0] = __builtin_amdgcn_mfma_f32_32x32x16_bf16(fa[s & 1][i], fb[s & 1][0], acc[i][0], 0, 0, 0);
;                     acc[i][1] = __builtin_amdgcn_mfma_f32_32x32x16_bf16(fa[s & 1][i], fb[s & 1][1], acc[i][1], 0, 0, 0);
;                 }
;                 __builtin_amdgcn_sched_barrier(0);
;             }
;             if (kt + 1 < nk) asm volatile("s_waitcnt vmcnt(0)" ::: "memory");
;             __builtin_amdgcn_s_barrier();
;             cur ^= 1;
	v_add3_u32 v191, s28, v151, v150
	v_add_u32_e32 v191, v191, v152
	v_add3_u32 v0, s28, v149, v150
	v_add_u32_e32 v0, v0, v152
	ds_read_b128 v[156:159], v191 offset:32768
	ds_read_b128 v[160:163], v191 offset:36864
	ds_read_b128 v[192:195], v0
	v_mfma_f32_32x32x16_bf16 v[82:97], v[196:199], v[208:211], v[82:97]
	v_mfma_f32_32x32x16_bf16 v[66:81], v[196:199], v[212:215], v[66:81]
	ds_read_b128 v[196:199], v0 offset:4096
	v_mfma_f32_32x32x16_bf16 v[50:65], v[200:203], v[208:211], v[50:65]
	v_mfma_f32_32x32x16_bf16 v[34:49], v[200:203], v[212:215], v[34:49]
	ds_read_b128 v[200:203], v0 offset:8192
	v_mfma_f32_32x32x16_bf16 v[18:33], v[204:207], v[208:211], v[18:33]
	v_mfma_f32_32x32x16_bf16 v[2:17], v[204:207], v[212:215], v[2:17]
	ds_read_b128 v[204:207], v0 offset:12288
	s_xor_b32 s34, s13, 1
	s_add_u32 s8, s8, 0x80
	s_addc_u32 s9, s9, 0
	s_cmpk_eq_i32 s8, 0x1580
	s_cbranch_scc0 .LBB0_1161
	s_waitcnt lgkmcnt(0)
	s_andn2_b64 vcc, exec, s[2:3]
	s_lshl_b32 s2, s34, 16
	s_cbranch_vccnz .LBB0_1153
	v_add_u32_e32 v0, s12, v143
	v_add_u32_e32 v136, s11, v143
	s_movk_i32 s3, 0x1600
	v_mad_i64_i32 v[136:137], s[8:9], v136, s3, v[132:133]
	v_mad_i64_i32 v[138:139], s[8:9], v0, s3, v[130:131]
	s_xor_b32 s3, s2, 0x10000
	v_add_u32_e32 v0, s3, v144
	v_add_u32_e32 v156, 0x8000, v0
	v_readfirstlane_b32 s3, v0
	s_mov_b32 m0, s3
	v_readfirstlane_b32 s3, v156
	v_add_u32_e32 v158, 0x2000, v0
	global_load_lds_dwordx4 v[138:139], off
	s_mov_b32 m0, s3
	s_mov_b64 s[8:9], 0x58000
	v_readfirstlane_b32 s3, v158
	v_add_u32_e32 v158, 0xa000, v0
	global_load_lds_dwordx4 v[136:137], off
	v_lshl_add_u64 v[156:157], v[138:139], 0, s[8:9]
	s_mov_b32 m0, s3
	v_readfirstlane_b32 s3, v158
	v_add_u32_e32 v158, 0x4000, v0
	global_load_lds_dwordx4 v[156:157], off
	v_lshl_add_u64 v[156:157], v[136:137], 0, s[8:9]
	s_mov_b32 m0, s3
	s_mov_b64 s[8:9], 0xb0000
	v_readfirstlane_b32 s3, v158
	v_add_u32_e32 v158, 0xc000, v0
	global_load_lds_dwordx4 v[156:157], off
	v_lshl_add_u64 v[156:157], v[138:139], 0, s[8:9]
	s_mov_b32 m0, s3
	v_readfirstlane_b32 s3, v158
	global_load_lds_dwordx4 v[156:157], off
	v_lshl_add_u64 v[156:157], v[136:137], 0, s[8:9]
	s_mov_b32 m0, s3
	s_mov_b64 s[8:9], 0x108000
	global_load_lds_dwordx4 v[156:157], off
	v_add_u32_e32 v156, 0x6000, v0
	v_add_u32_e32 v0, 0xe000, v0
	v_readfirstlane_b32 s3, v156
	v_lshl_add_u64 v[138:139], v[138:139], 0, s[8:9]
	s_mov_b32 m0, s3
	v_readfirstlane_b32 s3, v0
	global_load_lds_dwordx4 v[138:139], off
	v_lshl_add_u64 v[136:137], v[136:137], 0, s[8:9]
	s_mov_b32 m0, s3
	s_nop 0
	global_load_lds_dwordx4 v[136:137], off
	s_branch .LBB0_1153

; template <int EPI, int AMAP, int KOFFMODE, int K>
; __device__ __forceinline__ void gemm_phase(unsigned char* smem, const bf16_t* A, int lda, const bf16_t* Bt, int NT, const EpiArgs& ea) {
;     ...
;         for (int kt = 0; kt < nk; ++kt) {
;             if (kt + 1 < nk) GEMM_DMA(m0, n0, kt + 1, cur ^ 1);
;             else if (have_next) GEMM_DMA(m0n, n0n, 0, cur ^ 1);
;             const unsigned char* Ac = smem + cur * STGB + (wm * 128 + l31) * 128;
;             const unsigned char* Bc = smem + cur * STGB + 32768 + (wn * 64 + l31) * 128;
;             bf16x8 fa[2][4], fb[2][2];
;             fb[0][0] = *(const bf16x8*)(Bc + (((0) ^ yz) & 7) * 16);
;             fb[0][1] = *(const bf16x8*)(Bc + 32 * 128 + (((0) ^ yz) & 7) * 16);
; #pragma unroll
;             for (int i = 0; i < 4; ++i) fa[0][i] = *(const bf16x8*)(Ac + i * 32 * 128 + (((0) ^ yz) & 7) * 16);
; #pragma unroll
;             for (int s = 0; s < 4; ++s) {
;                 if (s < 3) {
;                     const int o_ = (((2 * (s + 1)) ^ yz) & 7) * 16;
;                     fb[(s + 1) & 1][0] = *(const bf16x8*)(Bc + o_);
;                     fb[(s + 1) & 1][1] = *(const bf16x8*)(Bc + 32 * 128 + o_);
; #pragma unroll
;                     for (int i = 0; i < 4; ++i) fa[(s + 1) & 1][i] = *(const bf16x8*)(Ac + i * 32 * 128 + o_);
;                 }
; #pragma unroll
;                 for (int i = 0; i < 4; ++i) {
;                     acc[i][0] = __builtin_amdgcn_mfma_f32_32x32x16_bf16(fa[s & 1][i], fb[s & 1][0], acc[i][0], 0, 0, 0);
;                     acc[i][1] = __builtin_amdgcn_mfma_f32_32x32x16_bf16(fa[s & 1][i], fb[s & 1][1], acc[i][1], 0, 0, 0);
;                 }
;                 __builtin_amdgcn_sched_barrier(0);
;             }
;             if (kt + 1 < nk) asm volatile("s_waitcnt vmcnt(0)" ::: "memory");
;             __builtin_amdgcn_s_barrier();
;             cur ^= 1;
;         }
.LBB0_1429:
	s_mov_b32 s9, s13
	s_lshl_b32 s13, s9, 16
	s_xor_b32 s12, s13, 0x10000
	v_readfirstlane_b32 vcc_lo, v143
	s_nop 0
	s_add_u32 vcc_lo, vcc_lo, s12
	v_add3_u32 v155, s13, v150, v149
	v_add_u32_e32 v155, v155, v152
	v_add3_u32 v0, s13, v147, v149
	v_add_u32_e32 v0, v0, v152
	ds_read_b128 v[208:211], v155 offset:32768
	ds_read_b128 v[212:215], v155 offset:36864
	s_waitcnt lgkmcnt(5)
	v_mfma_f32_32x32x16_bf16 v[114:129], v[192:195], v[156:159], v[114:129]
	s_add_u32 s14, s4, 0xe380080
	s_addc_u32 s15, s5, 0
	s_mov_b32 m0, vcc_lo
	v_lshl_add_u64 v[164:165], v[136:137], 0, s[14:15]
	global_load_lds_dwordx4 v[164:165], off
	v_mfma_f32_32x32x16_bf16 v[98:113], v[192:195], v[160:163], v[98:113]
	s_add_u32 s14, s4, 0xe3a0080
	s_addc_u32 s15, s5, 0
	s_add_u32 m0, vcc_lo, 0x2000
	v_lshl_add_u64 v[164:165], v[136:137], 0, s[14:15]
	global_load_lds_dwordx4 v[164:165], off
	ds_read_b128 v[192:195], v0
	s_waitcnt lgkmcnt(5)
	v_mfma_f32_32x32x16_bf16 v[82:97], v[196:199], v[156:159], v[82:97]
	s_add_u32 s14, s4, 0xe3c0080
	s_addc_u32 s15, s5, 0
	s_add_u32 m0, vcc_lo, 0x4000
	v_lshl_add_u64 v[164:165], v[136:137], 0, s[14:15]
	global_load_lds_dwordx4 v[164:165], off
	v_mfma_f32_32x32x16_bf16 v[66:81], v[196:199], v[160:163], v[66:81]
	s_add_u32 s14, s4, 0xe3e0080
	s_addc_u32 s15, s5, 0
	s_add_u32 m0, vcc_lo, 0x6000
	v_lshl_add_u64 v[164:165], v[136:137], 0, s[14:15]
	global_load_lds_dwordx4 v[164:165], off
	ds_read_b128 v[196:199], v0 offset:4096
	s_waitcnt lgkmcnt(5)
	v_mfma_f32_32x32x16_bf16 v[50:65], v[200:203], v[156:159], v[50:65]
	v_mfma_f32_32x32x16_bf16 v[34:49], v[200:203], v[160:163], v[34:49]
	ds_read_b128 v[200:203], v0 offset:8192
	s_waitcnt lgkmcnt(5)
	v_mfma_f32_32x32x16_bf16 v[18:33], v[204:207], v[156:159], v[18:33]
	v_mfma_f32_32x32x16_bf16 v[2:17], v[204:207], v[160:163], v[2:17]
	ds_read_b128 v[204:207], v0 offset:12288
	v_add3_u32 v155, s13, v150, v149
	v_add_u32_e32 v155, v155, v153
	v_add3_u32 v0, s13, v147, v149
	v_add_u32_e32 v0, v0, v153
	ds_read_b128 v[156:159], v155 offset:32768
	ds_read_b128 v[160:163], v155 offset:36864
	s_waitcnt lgkmcnt(5)
	v_mfma_f32_32x32x16_bf16 v[114:129], v[192:195], v[208:211], v[114:129]
	v_mfma_f32_32x32x16_bf16 v[98:113], v[192:195], v[212:215], v[98:113]
	s_add_u32 s14, s4, s20
	s_addc_u32 s15, s5, s21
	s_add_u32 m0, vcc_lo, 0x8000
	v_lshl_add_u64 v[164:165], v[138:139], 0, s[14:15]
	global_load_lds_dwordx4 v[164:165], off
	ds_read_b128 v[192:195], v0
	s_waitcnt lgkmcnt(5)
	v_mfma_f32_32x32x16_bf16 v[82:97], v[196:199], v[208:211], v[82:97]
	v_mfma_f32_32x32x16_bf16 v[66:81], v[196:199], v[212:215], v[66:81]
	s_add_u32 s14, s4, 0x820080
	s_addc_u32 s15, s5, 0
	s_add_u32 m0, vcc_lo, 0xa000
	v_lshl_add_u64 v[164:165], v[138:139], 0, s[14:15]
	global_load_lds_dwordx4 v[164:165], off
	ds_read_b128 v[196:199], v0 offset:4096
	s_waitcnt lgkmcnt(5)
	v_mfma_f32_32x32x16_bf16 v[50:65], v[200:203], v[208:211], v[50:65]
	v_mfma_f32_32x32x16_bf16 v[34:49], v[200:203], v[212:215], v[34:49]
	s_add_u32 s14, s4, s68
	s_addc_u32 s15, s5, s69
	s_add_u32 m0, vcc_lo, 0xc000
	v_lshl_add_u64 v[164:165], v[138:139], 0, s[14:15]
	global_load_lds_dwordx4 v[164:165], off
	ds_read_b128 v[200:203], v0 offset:8192
	s_waitcnt lgkmcnt(5)
	v_mfma_f32_32x32x16_bf16 v[18:33], v[204:207], v[208:211], v[18:33]
	v_mfma_f32_32x32x16_bf16 v[2:17], v[204:207], v[212:215], v[2:17]
	s_add_u32 s14, s4, 0x860080
	s_addc_u32 s15, s5, 0
	s_add_u32 m0, vcc_lo, 0xe000
	v_lshl_add_u64 v[164:165], v[138:139], 0, s[14:15]
	global_load_lds_dwordx4 v[164:165], off
	ds_read_b128 v[204:207], v0 offset:12288
	v_add3_u32 v155, s13, v150, v149
	v_add_u32_e32 v155, v155, v154
	v_add3_u32 v0, s13, v147, v149
	v_add_u32_e32 v0, v0, v154
	ds_read_b128 v[208:211], v155 offset:32768
	ds_read_b128 v[212:215], v155 offset:36864
	s_waitcnt lgkmcnt(5)
	v_mfma_f32_32x32x16_bf16 v[114:129], v[192:195], v[156:159], v[114:129]
	v_mfma_f32_32x32x16_bf16 v[98:113], v[192:195], v[160:163], v[98:113]
	ds_read_b128 v[192:195], v0
	s_waitcnt lgkmcnt(5)
	v_mfma_f32_32x32x16_bf16 v[82:97], v[196:199], v[156:159], v[82:97]
	v_mfma_f32_32x32x16_bf16 v[66:81], v[196:199], v[160:163], v[66:81]
	ds_read_b128 v[196:199], v0 offset:4096
	s_waitcnt lgkmcnt(5)
	v_mfma_f32_32x32x16_bf16 v[50:65], v[200:203], v[156:159], v[50:65]
	v_mfma_f32_32x32x16_bf16 v[34:49], v[200:203], v[160:163], v[34:49]
	ds_read_b128 v[200:203], v0 offset:8192
	s_waitcnt lgkmcnt(5)
	v_mfma_f32_32x32x16_bf16 v[18:33], v[204:207], v[156:159], v[18:33]
	v_mfma_f32_32x32x16_bf16 v[2:17], v[204:207], v[160:163], v[2:17]
	ds_read_b128 v[204:207], v0 offset:12288
	s_waitcnt lgkmcnt(3)
	v_mfma_f32_32x32x16_bf16 v[114:129], v[192:195], v[208:211], v[114:129]
	v_mfma_f32_32x32x16_bf16 v[98:113], v[192:195], v[212:215], v[98:113]
	s_waitcnt lgkmcnt(0)
	s_waitcnt vmcnt(0)
	s_barrier
; template <int EPI, int AMAP, int KOFFMODE, int K>
; __device__ __forceinline__ void gemm_phase(unsigned char* smem, const bf16_t* A, int lda, const bf16_t* Bt, int NT, const EpiArgs& ea) {
;     ...
;             for (int s = 0; s < 4; ++s) {
;                 if (s < 3) {
;                     const int o_ = (((2 * (s + 1)) ^ yz) & 7) * 16;
;                     fb[(s + 1) & 1][0] = *(const bf16x8*)(Bc + o_);
;                     fb[(s + 1) & 1][1] = *(const bf16x8*)(Bc + 32 * 128 + o_);
; #pragma unroll
;                     for (int i = 0; i < 4; ++i) fa[(s + 1) & 1][i] = *(const bf16x8*)(Ac + i * 32 * 128 + o_);
;                 }
; #pragma unroll
;                 for (int i = 0; i < 4; ++i) {
;                     acc[i][0] = __builtin_amdgcn_mfma_f32_32x32x16_bf16(fa[s & 1][i], fb[s & 1][0], acc[i][0], 0, 0, 0);
;                     acc[i][1] = __builtin_amdgcn_mfma_f32_32x32x16_bf16(fa[s & 1][i], fb[s & 1][1], acc[i][1], 0, 0, 0);
;                 }
;                 __builtin_amdgcn_sched_barrier(0);
;             }
;             if (kt + 1 < nk) asm volatile("s_waitcnt vmcnt(0)" ::: "memory");
;             __builtin_amdgcn_s_barrier();
;             cur ^= 1;
	v_add3_u32 v155, s12, v150, v149
	v_add_u32_e32 v155, v155, v151
	v_add3_u32 v0, s12, v147, v149
	v_add_u32_e32 v0, v0, v151
	ds_read_b128 v[156:159], v155 offset:32768
	ds_read_b128 v[160:163], v155 offset:36864
	ds_read_b128 v[192:195], v0
	v_mfma_f32_32x32x16_bf16 v[82:97], v[196:199], v[208:211], v[82:97]
	v_mfma_f32_32x32x16_bf16 v[66:81], v[196:199], v[212:215], v[66:81]
	ds_read_b128 v[196:199], v0 offset:4096
	v_mfma_f32_32x32x16_bf16 v[50:65], v[200:203], v[208:211], v[50:65]
	v_mfma_f32_32x32x16_bf16 v[34:49], v[200:203], v[212:215], v[34:49]
	ds_read_b128 v[200:203], v0 offset:8192
	v_mfma_f32_32x32x16_bf16 v[18:33], v[204:207], v[208:211], v[18:33]
	v_mfma_f32_32x32x16_bf16 v[2:17], v[204:207], v[212:215], v[2:17]
	ds_read_b128 v[204:207], v0 offset:12288
	s_xor_b32 s13, s9, 1
	s_add_u32 s4, s4, 0x80
	s_addc_u32 s5, s5, 0
	s_cmpk_eq_i32 s4, 0x780
	s_cbranch_scc0 .LBB0_1429
	s_waitcnt lgkmcnt(0)
	s_andn2_b64 vcc, exec, s[2:3]
	s_lshl_b32 s2, s13, 16
	s_cbranch_vccnz .LBB0_1421
	v_add_u32_e32 v136, s8, v142
	s_xor_b32 s3, s2, 0x10000
	v_ashrrev_i32_e32 v137, 31, v136
	v_add_u32_e32 v138, s7, v142
	v_add_u32_e32 v0, s3, v143
	v_lshlrev_b64 v[136:137], 11, v[136:137]
	v_ashrrev_i32_e32 v139, 31, v138
	v_add_u32_e32 v155, 0x8000, v0
	v_readfirstlane_b32 s3, v0
	v_lshlrev_b64 v[138:139], 11, v[138:139]
	v_lshl_add_u64 v[136:137], v[130:131], 0, v[136:137]
	s_mov_b32 m0, s3
	v_readfirstlane_b32 s3, v155
	v_add_u32_e32 v155, 0x2000, v0
	v_lshl_add_u64 v[138:139], v[132:133], 0, v[138:139]
	global_load_lds_dwordx4 v[136:137], off
	s_mov_b32 m0, s3
	s_mov_b64 s[4:5], 0x20000
	v_readfirstlane_b32 s3, v155
	v_add_u32_e32 v155, 0xa000, v0
	global_load_lds_dwordx4 v[138:139], off
	v_lshl_add_u64 v[156:157], v[136:137], 0, s[4:5]
	s_mov_b32 m0, s3
	v_readfirstlane_b32 s3, v155
	v_add_u32_e32 v155, 0x4000, v0
	global_load_lds_dwordx4 v[156:157], off
	v_lshl_add_u64 v[156:157], v[138:139], 0, s[4:5]
	s_mov_b32 m0, s3
	s_mov_b64 s[4:5], 0x40000
	v_readfirstlane_b32 s3, v155
	v_add_u32_e32 v155, 0xc000, v0
	global_load_lds_dwordx4 v[156:157], off
	v_lshl_add_u64 v[156:157], v[136:137], 0, s[4:5]
	s_mov_b32 m0, s3
	v_readfirstlane_b32 s3, v155
	v_add_u32_e32 v155, 0x6000, v0
	global_load_lds_dwordx4 v[156:157], off
	v_lshl_add_u64 v[156:157], v[138:139], 0, s[4:5]
	s_mov_b32 m0, s3
	s_mov_b64 s[4:5], 0x60000
	v_readfirstlane_b32 s3, v155
	v_add_u32_e32 v0, 0xe000, v0
	global_load_lds_dwordx4 v[156:157], off
	v_lshl_add_u64 v[136:137], v[136:137], 0, s[4:5]
	s_mov_b32 m0, s3
	v_readfirstlane_b32 s3, v0
	global_load_lds_dwordx4 v[136:137], off
	v_lshl_add_u64 v[136:137], v[138:139], 0, s[4:5]
	s_mov_b32 m0, s3
	s_nop 0
	global_load_lds_dwordx4 v[136:137], off
	s_branch .LBB0_1421
